# scan: one static priority raise (s_setprio 2) for the critical waves 0-3 on top of the double-buffered / barrier-free step
# baseline (speedup 1.0000x reference)
.LBB0_1144:
	s_ashr_i32 s5, s85, 2
	s_lshl_b32 s7, s85, 6
	s_lshl_b32 s6, s5, 8
	s_and_b32 s10, s7, 0x80
	s_or_b32 s6, s6, s10
	s_and_b32 s4, s85, 1
	s_bfe_i32 s8, s85, 0x10000
	s_ashr_i32 s12, s85, 4
	s_mul_hi_i32 s7, s6, 0x4200
	s_mulk_i32 s6, 0x4200
	s_and_b32 s11, s5, 3
	s_add_u32 s6, s56, s6
	s_addc_u32 s7, s57, s7
	s_cmp_eq_u32 s4, 0
	s_cselect_b64 s[4:5], -1, 0
	v_mov_b32_e32 v3, v148
	s_and_b64 s[14:15], s[4:5], exec
	s_mov_b32 s9, 0xc400000
	s_barrier
	s_cselect_b32 s9, s9, 0x10600000
	v_ashrrev_i32_e32 v14, 6, v3
	s_mov_b32 s13, 0x14800000
	v_add_u32_e32 v0, -4, v14
	s_cselect_b32 s13, s13, 0x1c800000
	s_cselect_b32 s86, 63, 0
	s_add_u32 s70, s54, s9
	v_lshrrev_b32_e32 v15, 1, v0
	v_and_b32_e32 v16, 1, v14
	s_addc_u32 s71, s55, 0
	v_cmp_gt_u32_e32 vcc, v16, v15
	s_add_u32 s13, s54, s13
	s_addc_u32 s14, s55, 0
	v_cndmask_b32_e64 v0, 0, 1, vcc
	v_cmp_lt_u32_e32 vcc, v16, v15
	s_lshl_b32 s87, s12, 8
	s_and_b32 s8, s8, 0xc0
	v_cndmask_b32_e64 v4, 0, 1, vcc
	s_add_i32 s87, s87, 0x10000
	v_cndmask_b32_e64 v17, v4, v0, s[4:5]
	s_or_b32 s15, s87, s8
	v_lshlrev_b32_e32 v4, 2, v3
	s_lshl_b32 s16, s8, 1
	s_or_b32 s8, s15, s86
	v_ashrrev_i32_e32 v149, 4, v3
	v_lshlrev_b32_e32 v0, 3, v3
	v_and_b32_e32 v21, 4, v4
	s_ashr_i32 s9, s8, 31
	v_and_b32_e32 v22, 0x78, v0
	v_add_u32_e32 v4, s15, v149
	v_ashrrev_i32_e32 v5, 31, v4
	v_lshl_or_b32 v136, s11, 7, v22
	s_lshl_b64 s[8:9], s[8:9], 10
	v_lshlrev_b64 v[4:5], 10, v[4:5]
	s_waitcnt vmcnt(11)
	v_lshlrev_b32_e32 v8, 1, v136
	s_add_u32 s8, s70, s8
	v_or_b32_e32 v4, v4, v8
	s_addc_u32 s9, s71, s9
	s_lshl_b32 s17, s11, 8
	v_add_u32_e32 v23, 0x200, v3
	s_waitcnt vmcnt(5)
	v_lshl_add_u64 v[6:7], s[76:77], 0, v[4:5]
	s_add_u32 s8, s8, s17
	v_ashrrev_i32_e32 v172, 4, v23
	s_addc_u32 s9, s9, 0
	v_lshlrev_b32_e32 v0, 1, v22
	global_load_dwordx4 v[138:141], v[6:7], off
	global_load_dwordx4 v[142:145], v0, s[8:9]
	v_add_u32_e32 v6, s15, v172
	v_ashrrev_i32_e32 v7, 31, v6
	v_lshlrev_b64 v[6:7], 10, v[6:7]
	v_lshl_add_u64 v[4:5], s[70:71], 0, v[4:5]
	v_or_b32_e32 v6, v6, v8
	v_lshl_add_u64 v[8:9], s[76:77], 0, v[6:7]
	global_load_dwordx4 v[156:159], v[4:5], off
	global_load_dwordx4 v[160:163], v[8:9], off
	v_lshl_add_u64 v[4:5], s[70:71], 0, v[6:7]
	global_load_dwordx4 v[164:167], v[4:5], off
	v_ashrrev_i32_e32 v12, 3, v3
	v_mov_b64_e32 v[4:5], s[6:7]
	v_mad_i64_i32 v[6:7], s[6:7], v12, s33, v[4:5]
	v_add_u32_e32 v12, 64, v12
	s_or_b32 s48, s16, 0x4000
	v_lshlrev_b32_e32 v24, 4, v3
	v_mad_i64_i32 v[4:5], s[6:7], v12, s33, v[4:5]
	v_lshl_add_u64 v[8:9], v[6:7], 0, s[48:49]
	v_and_b32_e32 v10, 0x70, v24
	v_mov_b32_e32 v11, v1
	v_lshl_add_u64 v[12:13], v[4:5], 0, s[48:49]
	v_lshl_add_u64 v[8:9], v[8:9], 0, v[10:11]
	v_lshl_add_u64 v[12:13], v[12:13], 0, v[10:11]
	global_load_dwordx4 v[128:131], v[8:9], off
	global_load_dwordx4 v[132:135], v[12:13], off
	v_ashrrev_i32_e32 v8, 7, v3
	v_lshlrev_b32_e32 v9, 1, v149
	v_lshrrev_b32_e32 v12, 1, v21
	v_and_b32_e32 v25, 14, v9
	v_lshlrev_b32_e32 v9, 7, v22
	v_xor_b32_e32 v13, v12, v8
	v_lshl_add_u32 v26, v13, 4, v9
	v_or_b32_e32 v13, 2, v22
	v_or_b32_e32 v29, 3, v22
	v_or_b32_e32 v32, 8, v22
	v_or_b32_e32 v35, 9, v22
	v_or_b32_e32 v38, 10, v22
	v_or_b32_e32 v22, 11, v22
	v_lshlrev_b32_e32 v27, 7, v13
	v_lshrrev_b32_e32 v13, 1, v13
	v_lshlrev_b32_e32 v30, 7, v29
	v_lshrrev_b32_e32 v29, 1, v29
	v_lshlrev_b32_e32 v33, 7, v32
	v_lshrrev_b32_e32 v32, 1, v32
	v_lshlrev_b32_e32 v36, 7, v35
	v_lshrrev_b32_e32 v35, 1, v35
	v_lshlrev_b32_e32 v39, 7, v38
	v_lshrrev_b32_e32 v38, 1, v38
	v_lshlrev_b32_e32 v41, 7, v22
	v_lshrrev_b32_e32 v22, 1, v22
	v_bitop3_b32 v28, v13, v8, 3 bitop3:0x6c
	v_bitop3_b32 v31, v29, v8, 3 bitop3:0x6c
	v_bitop3_b32 v34, v32, v8, 6 bitop3:0x6c
	v_bitop3_b32 v37, v35, v8, 6 bitop3:0x6c
	v_bitop3_b32 v40, v38, v8, 7 bitop3:0x6c
	v_bitop3_b32 v8, v22, v8, 7 bitop3:0x6c
	v_xor_b32_e32 v43, v149, v3
	v_lshl_add_u32 v42, v8, 4, v41
	v_lshlrev_b32_e32 v8, 8, v149
	v_lshlrev_b32_e32 v43, 4, v43
	s_add_u32 s8, s70, s17
	v_and_or_b32 v173, v43, s84, v8
	v_ashrrev_i32_e32 v8, 7, v23
	s_addc_u32 s9, s71, 0
	v_lshl_add_u64 v[154:155], v[4:5], 0, v[10:11]
	s_lshl_b32 s88, s12, 13
	v_lshlrev_b32_e32 v4, 5, v3
	v_lshlrev_b32_e32 v5, 2, v21
	s_movk_i32 s12, 0xffc0
	v_xor_b32_e32 v12, v12, v8
	s_nop 0
	v_lshl_add_u32 v43, v12, 4, v9
	v_bitop3_b32 v9, v13, v8, 3 bitop3:0x6c
	v_add_u32_e32 v176, 0x16000, v4
	v_and_b32_e32 v4, 1, v17
	v_lshl_add_u32 v28, v28, 4, v27
	v_lshl_add_u32 v27, v9, 4, v27
	v_bitop3_b32 v9, v29, v8, 3 bitop3:0x6c
	v_cmp_eq_u32_e32 vcc, 1, v4
	v_lshl_add_u32 v29, v9, 4, v30
	v_bitop3_b32 v9, v32, v8, 6 bitop3:0x6c
	s_xor_b64 s[78:79], vcc, -1
	s_lshl_b32 s11, s11, 9
	v_lshl_add_u32 v31, v31, 4, v30
	v_lshl_add_u32 v30, v9, 4, v33
	v_bitop3_b32 v9, v35, v8, 6 bitop3:0x6c
	s_add_u32 s11, s13, s11
	v_and_b32_e32 v18, 31, v3
	v_lshl_add_u32 v32, v9, 4, v36
	v_bitop3_b32 v9, v38, v8, 7 bitop3:0x6c
	v_lshl_add_u64 v[146:147], s[8:9], 0, v[0:1]
	v_lshlrev_b32_e32 v0, 5, v14
	s_addc_u32 s12, s14, 0
	s_lshl_b32 s10, s10, 1
	v_lshrrev_b32_e32 v2, 5, v3
	v_bfe_u32 v19, v3, 5, 1
	v_bfe_u32 v20, v3, 1, 3
	v_lshl_add_u32 v34, v34, 4, v33
	v_lshl_add_u32 v33, v9, 4, v39
	v_xor_b32_e32 v9, v172, v3
	v_and_b32_e32 v35, 0xffffff80, v24
	v_bitop3_b32 v24, v24, s51, v3 bitop3:0x48
	v_cmp_gt_i32_e64 s[6:7], 16, v3
	v_lshl_add_u64 v[152:153], v[6:7], 0, v[10:11]
	v_and_b32_e32 v0, 0x60, v0
	v_lshlrev_b32_e32 v177, 8, v18
	v_and_b32_e32 v6, 15, v3
	v_lshlrev_b32_e32 v3, 1, v3
	s_add_u32 s10, s11, s10
	v_lshl_or_b32 v179, v16, 13, v177
	v_lshl_or_b32 v7, v16, 5, v18
	v_and_b32_e32 v16, 14, v3
	v_or_b32_e32 v3, v0, v18
	s_addc_u32 s11, s12, 0
	v_lshlrev_b32_e32 v0, 1, v0
	v_lshl_add_u64 v[4:5], s[10:11], 0, v[0:1]
	v_lshlrev_b32_e32 v0, 1, v18
	v_lshl_add_u64 v[4:5], v[4:5], 0, v[0:1]
	v_bitop3_b32 v0, v2, v6, 1 bitop3:0x6c
	v_lshlrev_b32_e32 v184, 4, v0
	v_bitop3_b32 v0, v19, v6, 2 bitop3:0x36
	v_lshlrev_b32_e32 v185, 4, v0
	v_bitop3_b32 v0, v19, v6, 4 bitop3:0x36
	v_lshlrev_b32_e32 v186, 4, v0
	v_bitop3_b32 v0, v19, v6, 6 bitop3:0x36
	v_lshlrev_b32_e32 v187, 4, v0
	v_bitop3_b32 v0, v19, v6, 8 bitop3:0x36
	v_bitop3_b32 v8, v22, v8, 7 bitop3:0x6c
	v_lshlrev_b32_e32 v188, 4, v0
	v_bitop3_b32 v0, v19, v6, 10 bitop3:0x36
	v_lshl_add_u32 v22, v8, 4, v41
	v_lshlrev_b32_e32 v8, 8, v172
	v_lshlrev_b32_e32 v9, 4, v9
	v_lshlrev_b32_e32 v189, 4, v0
	v_bitop3_b32 v0, v19, v6, 12 bitop3:0x36
	v_and_or_b32 v174, v9, s84, v8
	v_lshlrev_b32_e32 v8, 2, v19
	v_lshlrev_b32_e32 v190, 4, v0
	v_bitop3_b32 v0, v19, v6, 14 bitop3:0x36
	v_lshlrev_b32_e32 v191, 4, v0
	v_lshl_or_b32 v0, v15, 5, v8
	v_cmp_le_u32_e32 vcc, v7, v0
	v_lshlrev_b32_e32 v180, 7, v3
	v_lshrrev_b32_e32 v9, 3, v7
	v_cndmask_b32_e64 v3, 0, 1, vcc
	v_cmp_ge_u32_e32 vcc, v7, v0
	v_lshlrev_b32_e32 v8, 4, v9
	v_lshlrev_b32_e32 v181, 7, v18
	v_cndmask_b32_e64 v6, 0, 1, vcc
	v_cndmask_b32_e64 v3, v6, v3, s[4:5]
	v_and_b32_e32 v3, 1, v3
	v_cmp_eq_u32_e64 s[10:11], 1, v3
	v_lshlrev_b32_e32 v3, 7, v0
	v_lshlrev_b32_e32 v6, 5, v19
	v_bitop3_b32 v3, v3, v8, v6 bitop3:0xf6
	v_add_u32_e32 v17, 0x14000, v3
	v_or_b32_e32 v3, 1, v0
	v_cmp_gt_u32_e32 vcc, v7, v0
	v_lshl_add_u32 v37, v37, 4, v36
	v_lshl_add_u32 v40, v40, 4, v39
	v_cndmask_b32_e64 v10, 0, 1, vcc
	v_cmp_le_u32_e32 vcc, v7, v3
	v_lshlrev_b32_e32 v3, 7, v3
	v_bitop3_b32 v3, v3, v8, v6 bitop3:0xf6
	v_cndmask_b32_e64 v11, 0, 1, vcc
	v_cndmask_b32_e64 v10, v10, v11, s[4:5]
	v_add_u32_e32 v18, 0x14000, v3
	v_or_b32_e32 v3, 2, v0
	v_and_b32_e32 v10, 1, v10
	v_cmp_le_u32_e32 vcc, v7, v3
	v_cmp_eq_u32_e64 s[12:13], 1, v10
	v_lshlrev_b32_e32 v23, 1, v172
	v_cndmask_b32_e64 v10, 0, 1, vcc
	v_cmp_ge_u32_e32 vcc, v7, v3
	v_and_b32_e32 v23, 14, v23
	v_cmp_gt_i32_e64 s[8:9], 4, v14
	v_cndmask_b32_e64 v11, 0, 1, vcc
	v_cndmask_b32_e64 v10, v11, v10, s[4:5]
	v_and_b32_e32 v10, 1, v10
	v_cmp_eq_u32_e64 s[14:15], 1, v10
	v_lshrrev_b32_e32 v10, 1, v3
	v_bitop3_b32 v10, v10, v9, 3 bitop3:0x6c
	v_lshlrev_b32_e32 v10, 4, v10
	v_lshl_or_b32 v3, v3, 7, v10
	v_add_u32_e32 v21, 0x14000, v3
	v_or_b32_e32 v3, 3, v0
	v_cmp_le_u32_e32 vcc, v7, v3
	v_lshl_or_b32 v178, v15, 13, v177
	v_mov_b32_e32 v14, v1
	v_cndmask_b32_e64 v10, 0, 1, vcc
	v_cmp_ge_u32_e32 vcc, v7, v3
	v_mov_b32_e32 v15, v1
	v_lshl_or_b32 v183, v19, 4, v137
	v_cndmask_b32_e64 v11, 0, 1, vcc
	v_cndmask_b32_e64 v10, v11, v10, s[4:5]
	v_and_b32_e32 v10, 1, v10
	v_cmp_eq_u32_e64 s[16:17], 1, v10
	v_lshrrev_b32_e32 v10, 1, v3
	v_bitop3_b32 v10, v10, v9, 3 bitop3:0x6c
	v_lshlrev_b32_e32 v10, 4, v10
	v_lshl_or_b32 v3, v3, 7, v10
	v_add_u32_e32 v36, 0x14000, v3
	v_or_b32_e32 v3, 8, v0
	v_cmp_le_u32_e32 vcc, v7, v3
	v_mov_b32_e32 v12, v1
	v_mov_b32_e32 v13, v1
	v_cndmask_b32_e64 v10, 0, 1, vcc
	v_cmp_ge_u32_e32 vcc, v7, v3
	v_add_u32_e32 v197, v26, v25
	v_add_u32_e32 v198, v28, v25
	v_cndmask_b32_e64 v11, 0, 1, vcc
	v_cndmask_b32_e64 v10, v11, v10, s[4:5]
	v_and_b32_e32 v10, 1, v10
	v_cmp_eq_u32_e64 s[18:19], 1, v10
	v_lshrrev_b32_e32 v10, 1, v3
	v_bitop3_b32 v10, v10, v9, 6 bitop3:0x6c
	v_lshlrev_b32_e32 v10, 4, v10
	v_lshl_or_b32 v3, v3, 7, v10
	v_add_u32_e32 v38, 0x14000, v3
	v_or_b32_e32 v3, 9, v0
	v_cmp_le_u32_e32 vcc, v7, v3
	v_add_u32_e32 v199, v31, v25
	v_add_u32_e32 v200, v34, v25
	v_cndmask_b32_e64 v10, 0, 1, vcc
	v_cmp_ge_u32_e32 vcc, v7, v3
	v_add_u32_e32 v201, v37, v25
	v_add_u32_e32 v202, v40, v25
	v_cndmask_b32_e64 v11, 0, 1, vcc
	v_cndmask_b32_e64 v10, v11, v10, s[4:5]
	v_and_b32_e32 v10, 1, v10
	v_cmp_eq_u32_e64 s[20:21], 1, v10
	v_lshrrev_b32_e32 v10, 1, v3
	v_bitop3_b32 v10, v10, v9, 6 bitop3:0x6c
	v_lshlrev_b32_e32 v10, 4, v10
	v_lshl_or_b32 v3, v3, 7, v10
	v_add_u32_e32 v39, 0x14000, v3
	v_or_b32_e32 v3, 10, v0
	v_cmp_le_u32_e32 vcc, v7, v3
	v_add_u32_e32 v203, v42, v25
	v_add_u32_e32 v204, v43, v23
	v_cndmask_b32_e64 v10, 0, 1, vcc
	v_cmp_ge_u32_e32 vcc, v7, v3
	v_add_u32_e32 v205, v27, v23
	v_add_u32_e32 v206, v29, v23
	v_cndmask_b32_e64 v11, 0, 1, vcc
	v_cndmask_b32_e64 v10, v11, v10, s[4:5]
	v_and_b32_e32 v10, 1, v10
	v_cmp_eq_u32_e64 s[22:23], 1, v10
	v_lshrrev_b32_e32 v10, 1, v3
	v_bitop3_b32 v10, v10, v9, 7 bitop3:0x6c
	v_lshlrev_b32_e32 v10, 4, v10
	v_lshl_or_b32 v3, v3, 7, v10
	v_add_u32_e32 v41, 0x14000, v3
	v_or_b32_e32 v3, 11, v0
	v_cmp_le_u32_e32 vcc, v7, v3
	v_add_u32_e32 v207, v30, v23
	v_add_u32_e32 v208, v32, v23
	v_cndmask_b32_e64 v10, 0, 1, vcc
	v_cmp_ge_u32_e32 vcc, v7, v3
	v_add_u32_e32 v209, v33, v23
	v_add_u32_e32 v210, v22, v23
	v_cndmask_b32_e64 v11, 0, 1, vcc
	v_cndmask_b32_e64 v10, v11, v10, s[4:5]
	v_and_b32_e32 v10, 1, v10
	v_cmp_eq_u32_e64 s[24:25], 1, v10
	v_lshrrev_b32_e32 v10, 1, v3
	v_bitop3_b32 v10, v10, v9, 7 bitop3:0x6c
	v_lshlrev_b32_e32 v10, 4, v10
	v_lshl_or_b32 v3, v3, 7, v10
	v_add_u32_e32 v44, 0x14000, v3
	v_or_b32_e32 v3, 16, v0
	v_cmp_le_u32_e32 vcc, v7, v3
	v_add_u32_e32 v211, v35, v24
	v_add_u32_e32 v212, v17, v16
	v_cndmask_b32_e64 v10, 0, 1, vcc
	v_cmp_ge_u32_e32 vcc, v7, v3
	v_lshlrev_b32_e32 v3, 7, v3
	v_bitop3_b32 v3, v3, v8, v6 bitop3:0xf6
	v_cndmask_b32_e64 v11, 0, 1, vcc
	v_cndmask_b32_e64 v10, v11, v10, s[4:5]
	v_add_u32_e32 v45, 0x14000, v3
	v_or_b32_e32 v3, 17, v0
	v_and_b32_e32 v10, 1, v10
	v_cmp_le_u32_e32 vcc, v7, v3
	v_cmp_eq_u32_e64 s[26:27], 1, v10
	v_add_u32_e32 v213, v18, v16
	v_cndmask_b32_e64 v10, 0, 1, vcc
	v_cmp_ge_u32_e32 vcc, v7, v3
	v_lshlrev_b32_e32 v3, 7, v3
	v_bitop3_b32 v3, v3, v8, v6 bitop3:0xf6
	v_add_u32_e32 v46, 0x14000, v3
	v_or_b32_e32 v3, 18, v0
	v_cndmask_b32_e64 v11, 0, 1, vcc
	v_cmp_le_u32_e32 vcc, v7, v3
	v_cndmask_b32_e64 v10, v11, v10, s[4:5]
	v_and_b32_e32 v10, 1, v10
	v_cndmask_b32_e64 v6, 0, 1, vcc
	v_cmp_ge_u32_e32 vcc, v7, v3
	v_cmp_eq_u32_e64 s[28:29], 1, v10
	v_mov_b32_e32 v10, v1
	v_cndmask_b32_e64 v8, 0, 1, vcc
	v_cndmask_b32_e64 v6, v8, v6, s[4:5]
	v_and_b32_e32 v6, 1, v6
	v_cmp_eq_u32_e64 s[30:31], 1, v6
	v_lshrrev_b32_e32 v6, 1, v3
	v_bitop3_b32 v6, v6, v9, 3 bitop3:0x6c
	v_lshlrev_b32_e32 v6, 4, v6
	v_lshl_or_b32 v3, v3, 7, v6
	v_add_u32_e32 v47, 0x14000, v3
	v_or_b32_e32 v3, 19, v0
	v_cmp_le_u32_e32 vcc, v7, v3
	v_mov_b32_e32 v11, v1
	v_add_u32_e32 v214, v21, v16
	v_cndmask_b32_e64 v6, 0, 1, vcc
	v_cmp_ge_u32_e32 vcc, v7, v3
	v_add_u32_e32 v215, v36, v16
	v_add_u32_e32 v216, v38, v16
	v_cndmask_b32_e64 v8, 0, 1, vcc
	v_cndmask_b32_e64 v6, v8, v6, s[4:5]
	v_and_b32_e32 v6, 1, v6
	v_cmp_eq_u32_e64 s[34:35], 1, v6
	v_lshrrev_b32_e32 v6, 1, v3
	v_bitop3_b32 v6, v6, v9, 3 bitop3:0x6c
	v_lshlrev_b32_e32 v6, 4, v6
	v_lshl_or_b32 v3, v3, 7, v6
	v_add_u32_e32 v48, 0x14000, v3
	v_or_b32_e32 v3, 24, v0
	v_cmp_le_u32_e32 vcc, v7, v3
	v_add_u32_e32 v217, v39, v16
	v_add_u32_e32 v218, v41, v16
	v_cndmask_b32_e64 v6, 0, 1, vcc
	v_cmp_ge_u32_e32 vcc, v7, v3
	v_add_u32_e32 v219, v44, v16
	v_add_u32_e32 v220, v45, v16
	v_cndmask_b32_e64 v8, 0, 1, vcc
	v_cndmask_b32_e64 v6, v8, v6, s[4:5]
	v_and_b32_e32 v6, 1, v6
	v_cmp_eq_u32_e64 s[36:37], 1, v6
	v_lshrrev_b32_e32 v6, 1, v3
	v_bitop3_b32 v6, v6, v9, 6 bitop3:0x6c
	v_lshlrev_b32_e32 v6, 4, v6
	v_lshl_or_b32 v3, v3, 7, v6
	v_add_u32_e32 v49, 0x14000, v3
	v_or_b32_e32 v3, 25, v0
	v_cmp_le_u32_e32 vcc, v7, v3
	v_add_u32_e32 v221, v46, v16
	v_add_u32_e32 v222, v47, v16
	v_cndmask_b32_e64 v6, 0, 1, vcc
	v_cmp_ge_u32_e32 vcc, v7, v3
	v_add_u32_e32 v223, v48, v16
	v_add_u32_e32 v224, v49, v16
	v_cndmask_b32_e64 v8, 0, 1, vcc
	v_cndmask_b32_e64 v6, v8, v6, s[4:5]
	v_and_b32_e32 v6, 1, v6
	v_cmp_eq_u32_e64 s[38:39], 1, v6
	v_lshrrev_b32_e32 v6, 1, v3
	v_bitop3_b32 v6, v6, v9, 6 bitop3:0x6c
	v_lshlrev_b32_e32 v6, 4, v6
	v_lshl_or_b32 v3, v3, 7, v6
	v_add_u32_e32 v50, 0x14000, v3
	v_or_b32_e32 v3, 26, v0
	v_cmp_le_u32_e32 vcc, v7, v3
	v_or_b32_e32 v0, 27, v0
	v_add_u32_e32 v225, v50, v16
	v_cndmask_b32_e64 v6, 0, 1, vcc
	v_cmp_ge_u32_e32 vcc, v7, v3
	v_or_b32_e32 v182, 0x14000, v181
	s_waitcnt vmcnt(16)
	v_mov_b64_e32 v[170:171], 0
	v_cndmask_b32_e64 v8, 0, 1, vcc
	v_cndmask_b32_e64 v6, v8, v6, s[4:5]
	v_and_b32_e32 v6, 1, v6
	v_cmp_eq_u32_e64 s[40:41], 1, v6
	v_lshrrev_b32_e32 v6, 1, v3
	v_bitop3_b32 v6, v6, v9, 7 bitop3:0x6c
	v_lshlrev_b32_e32 v6, 4, v6
	v_lshl_or_b32 v3, v3, 7, v6
	v_cmp_le_u32_e32 vcc, v7, v0
	v_add_u32_e32 v51, 0x14000, v3
	v_mov_b32_e32 v8, v1
	v_cndmask_b32_e64 v3, 0, 1, vcc
	v_cmp_ge_u32_e32 vcc, v7, v0
	v_mov_b32_e32 v7, v1
	v_add_u32_e32 v226, v51, v16
	v_cndmask_b32_e64 v6, 0, 1, vcc
	v_cndmask_b32_e64 v3, v6, v3, s[4:5]
	v_and_b32_e32 v3, 1, v3
	v_cmp_eq_u32_e64 s[42:43], 1, v3
	v_lshrrev_b32_e32 v3, 1, v0
	v_bitop3_b32 v3, v3, v9, 7 bitop3:0x6c
	v_lshlrev_b32_e32 v3, 4, v3
	v_lshl_or_b32 v0, v0, 7, v3
	v_add_u32_e32 v52, 0x14000, v0
	v_bitop3_b32 v0, v2, v20, 1 bitop3:0x6c
	v_lshlrev_b32_e32 v192, 4, v0
	v_bitop3_b32 v0, v19, v20, 2 bitop3:0x36
	v_lshlrev_b32_e32 v193, 4, v0
	v_bitop3_b32 v0, v19, v20, 4 bitop3:0x36
	v_lshlrev_b32_e32 v195, 4, v0
	v_bitop3_b32 v0, v19, v20, 6 bitop3:0x36
	v_lshlrev_b32_e32 v196, 4, v0
	v_lshlrev_b32_e32 v0, 13, v19
	v_lshl_add_u64 v[168:169], v[4:5], 0, v[0:1]
	v_mov_b32_e32 v0, v1
	v_mov_b32_e32 v2, v1
	v_mov_b32_e32 v3, v1
	v_mov_b32_e32 v4, v1
	v_mov_b32_e32 v5, v1
	v_mov_b32_e32 v6, v1
	v_mov_b32_e32 v9, v1
	v_add_u32_e32 v227, v52, v16
	v_mov_b64_e32 v[30:31], v[14:15]
	v_mov_b64_e32 v[46:47], v[14:15]
	v_mov_b64_e32 v[62:63], v[14:15]
	v_mov_b64_e32 v[78:79], v[14:15]
	s_movk_i32 s89, 0x82
	v_mov_b64_e32 v[28:29], v[12:13]
	v_mov_b64_e32 v[26:27], v[10:11]
	v_mov_b64_e32 v[24:25], v[8:9]
	v_mov_b64_e32 v[22:23], v[6:7]
	v_mov_b64_e32 v[20:21], v[4:5]
	v_mov_b64_e32 v[18:19], v[2:3]
	v_mov_b64_e32 v[16:17], v[0:1]
	v_mov_b64_e32 v[44:45], v[12:13]
	v_mov_b64_e32 v[42:43], v[10:11]
	v_mov_b64_e32 v[40:41], v[8:9]
	v_mov_b64_e32 v[38:39], v[6:7]
	v_mov_b64_e32 v[36:37], v[4:5]
	v_mov_b64_e32 v[34:35], v[2:3]
	v_mov_b64_e32 v[32:33], v[0:1]
	v_mov_b64_e32 v[60:61], v[12:13]
	v_mov_b64_e32 v[58:59], v[10:11]
	v_mov_b64_e32 v[56:57], v[8:9]
	v_mov_b64_e32 v[54:55], v[6:7]
	v_mov_b64_e32 v[52:53], v[4:5]
	v_mov_b64_e32 v[50:51], v[2:3]
	v_mov_b64_e32 v[48:49], v[0:1]
	v_mov_b64_e32 v[76:77], v[12:13]
	v_mov_b64_e32 v[74:75], v[10:11]
	v_mov_b64_e32 v[72:73], v[8:9]
	v_mov_b64_e32 v[70:71], v[6:7]
	v_mov_b64_e32 v[68:69], v[4:5]
	v_mov_b64_e32 v[66:67], v[2:3]
	v_mov_b64_e32 v[64:65], v[0:1]
	s_mov_b32 s81, s49
	v_mov_b64_e32 v[6:7], 0
	v_mov_b64_e32 v[8:9], 0
	v_mov_b64_e32 v[10:11], 0
	v_and_b32_e32 v113, 15, v148
	v_bfe_u32 v114, v148, 5, 1
	v_lshlrev_b32_e32 v115, 2, v113
	v_and_b32_e32 v115, 12, v115
	v_lshrrev_b32_e32 v116, 2, v113
	v_or_b32_e32 v115, v115, v116
	v_xor_b32_e32 v115, v115, v114
	v_xor_b32_e32 v116, 0, v115
	v_lshlrev_b32_e32 v184, 4, v116
	v_xor_b32_e32 v116, 2, v115
	v_lshlrev_b32_e32 v185, 4, v116
	v_xor_b32_e32 v116, 4, v115
	v_lshlrev_b32_e32 v186, 4, v116
	v_xor_b32_e32 v116, 6, v115
	v_lshlrev_b32_e32 v187, 4, v116
	v_xor_b32_e32 v116, 8, v115
	v_lshlrev_b32_e32 v188, 4, v116
	v_xor_b32_e32 v116, 10, v115
	v_lshlrev_b32_e32 v189, 4, v116
	v_xor_b32_e32 v116, 12, v115
	v_lshlrev_b32_e32 v190, 4, v116
	v_xor_b32_e32 v116, 14, v115
	v_lshlrev_b32_e32 v191, 4, v116
	v_lshlrev_b32_e32 v116, 2, v149
	v_and_b32_e32 v116, 12, v116
	v_bfe_u32 v117, v149, 2, 2
	v_or_b32_e32 v116, v116, v117
	v_and_b32_e32 v117, 14, v113
	v_xor_b32_e32 v116, v116, v117
	v_lshlrev_b32_e32 v116, 4, v116
	v_lshl_or_b32 v173, v149, 8, v116
	v_and_b32_e32 v117, 1, v113
	v_lshl_or_b32 v173, v117, 3, v173
	v_xor_b32_e32 v174, 16, v173
	v_mov_b64_e32 v[232:233], 0
	v_mov_b64_e32 v[234:235], 0
	v_and_b32_e32 v116, 3, v148
	v_bfe_u32 v117, v148, 2, 2
	v_bfe_u32 v118, v148, 4, 1
	v_and_b32_e32 v119, 1, v116
	v_lshl_or_b32 v119, v118, 1, v119
	v_lshlrev_b32_e32 v120, 1, v114
	v_xor_b32_e32 v119, v119, v120
	v_lshl_or_b32 v119, v117, 2, v119
	v_lshlrev_b32_e32 v119, 4, v119
	v_lshrrev_b32_e32 v120, 1, v116
	v_lshl_or_b32 v119, v120, 3, v119
	v_lshl_add_u32 v120, v114, 3, v117
	v_lshl_or_b32 v119, v120, 8, v119
	v_add_u32_e32 v197, 0x4000, v119
	v_xor_b32_e32 v198, 64, v197
	v_xor_b32_e32 v199, 0x80, v197
	v_xor_b32_e32 v200, 0xc0, v197
	v_xor_b32_e32 v201, 16, v197
	v_xor_b32_e32 v202, 16, v198
	v_xor_b32_e32 v203, 16, v199
	v_xor_b32_e32 v204, 16, v200
	v_add_u32_e32 v182, 0x4000, v182
	v_add_u32_e32 v176, 0x4000, v176
	v_add_u32_e32 v183, 0x4000, v183
	v_add_u32_e32 v212, 0x4000, v212
	v_add_u32_e32 v213, 0x4000, v213
	v_add_u32_e32 v214, 0x4000, v214
	v_add_u32_e32 v215, 0x4000, v215
	v_add_u32_e32 v216, 0x4000, v216
	v_add_u32_e32 v217, 0x4000, v217
	v_add_u32_e32 v218, 0x4000, v218
	v_add_u32_e32 v219, 0x4000, v219
	v_add_u32_e32 v220, 0x4000, v220
	v_add_u32_e32 v221, 0x4000, v221
	v_add_u32_e32 v222, 0x4000, v222
	v_add_u32_e32 v223, 0x4000, v223
	v_add_u32_e32 v224, 0x4000, v224
	v_add_u32_e32 v225, 0x4000, v225
	v_add_u32_e32 v226, 0x4000, v226
	v_add_u32_e32 v227, 0x4000, v227
	s_cmp_lg_u64 s[8:9], 0
	s_cbranch_scc0 .Lscan_noprio
	s_setprio 2
.Lscan_noprio:
	s_branch .LBB0_1146
.LBB0_1145:
	s_or_b64 exec, exec, s[44:45]
	s_add_i32 s89, s89, -1
	s_mov_b32 s81, s90
	s_and_b64 vcc, exec, s[82:83]
	s_cbranch_vccnz .Lscan_nob3
	s_barrier

.LBB0_1174:
	s_setprio 0
	s_and_b64 s[4:5], s[46:47], exec
	s_cselect_b32 s3, 0x80, 0
	v_readlane_b32 s76, v255, 1
	s_cmp_lt_i32 s2, s3
	v_readlane_b32 s78, v255, 3
	v_readlane_b32 s79, v255, 4
	v_readlane_b32 s80, v255, 5
	v_readlane_b32 s81, v255, 6
	v_readlane_b32 s82, v255, 7
	v_readlane_b32 s83, v255, 8
	v_readlane_b32 s84, v255, 9
	v_readlane_b32 s85, v255, 10
	v_readlane_b32 s86, v255, 11
	v_readlane_b32 s87, v255, 12
	v_readlane_b32 s88, v255, 13
	v_readlane_b32 s89, v255, 14
	v_readlane_b32 s90, v255, 15
	v_readlane_b32 s91, v255, 16
	v_readlane_b32 s77, v255, 2
	s_cbranch_scc1 .LBB0_1207
	s_sub_i32 s6, s50, s3
	s_sub_i32 s8, s2, s3
	s_cmpk_gt_i32 s8, 0x3ff
	s_cbranch_scc1 .LBB0_1192
	s_add_u32 s3, s54, 0x1080000
	s_addc_u32 s7, s55, 0
	s_cmp_lg_u64 s[52:53], 0
	s_cselect_b64 s[10:11], -1, 0
	s_add_u32 s9, s54, 0x4000080
	s_addc_u32 s22, s55, 0
	s_mov_b32 s23, 0x1ffff0
	s_waitcnt vmcnt(1)
	v_mov_b32_e32 v129, 0
	s_movk_i32 s24, 0x3000
	s_mov_b64 s[12:13], 0x80
	s_movk_i32 s25, 0x100
	s_movk_i32 s26, 0x110
	s_mov_b32 s27, s2
	s_mov_b32 s28, s8
	s_branch .LBB0_1178
